# grid barrier: acquire L1 invalidate issued before the wait loop (CU quiescent, polls are sc1) instead of after the release
# speedup vs baseline: 1.0842x; 1.0071x over previous
; __device__ __forceinline__ unsigned xb_ld(unsigned* p)              { return __hip_atomic_load(p, __ATOMIC_RELAXED, __HIP_MEMORY_SCOPE_AGENT); }
; __device__ __forceinline__ unsigned xb_add(unsigned* p, unsigned v) { return __hip_atomic_fetch_add(p, v, __ATOMIC_RELAXED, __HIP_MEMORY_SCOPE_AGENT); }
; #define XB_SPIN(cond, bar) do { unsigned _sp = 0; while (cond) { __builtin_amdgcn_s_sleep(1); \
;     if ((++_sp & 255u) == 0u) { if (xb_ld(&(bar)[XB_TMO])) break; if (_sp > XB_SPIN_CAP) { atomicAdd(&(bar)[XB_TMO], 1u); break; } } } } while (0)
; __device__ __forceinline__ void xcd_barrier(const XcdBarrier& b) {
;     ...
;         const unsigned old = xb_add(&bar[XB_XSUB(b.x)], 1u);
;         const unsigned gen = old / nloc;
;         if (old + 1u == (gen + 1u) * nloc) {
;             __builtin_amdgcn_fence(__ATOMIC_RELEASE, "agent");
;             asm volatile("s_waitcnt vmcnt(0)" ::: "memory");
;             const unsigned og = xb_add(&bar[XB_TOP], 1u);
;             const unsigned tg = og / nx;
;             if (og + 1u == (tg + 1u) * nx) xb_add(&bar[XB_TOPGEN], 1u);
;             else XB_SPIN(xb_ld(&bar[XB_TOPGEN]) == tg, bar);
;             __builtin_amdgcn_fence(__ATOMIC_ACQUIRE, "agent");
;             xb_add(&bar[XB_XGEN(b.x)], 1u);
;             asm volatile("s_waitcnt vmcnt(0)" ::: "memory");
;         } else {
;             XB_SPIN(xb_ld(&bar[XB_XGEN(b.x)]) == gen, bar);
;             __builtin_amdgcn_fence(__ATOMIC_ACQUIRE, "agent");
.LBB0_66:
	s_or_b64 exec, exec, s[8:9]
	v_cvt_f32_u32_e32 v4, v2
	s_waitcnt vmcnt(0)
	v_readfirstlane_b32 s3, v3
	v_sub_u32_e32 v3, 0, v2
	v_rcp_iflag_f32_e32 v4, v4
	v_add_u32_e32 v5, s3, v1
	v_mul_f32_e32 v4, 0x4f7ffffe, v4
	v_cvt_u32_f32_e32 v4, v4
	v_mul_lo_u32 v1, v3, v4
	v_mul_hi_u32 v1, v4, v1
	v_add_u32_e32 v1, v4, v1
	v_mul_hi_u32 v1, v5, v1
	v_mul_lo_u32 v3, v1, v2
	v_sub_u32_e32 v3, v5, v3
	v_add_u32_e32 v4, 1, v1
	v_cmp_ge_u32_e32 vcc, v3, v2
	s_nop 1
	v_cndmask_b32_e32 v1, v1, v4, vcc
	v_sub_u32_e32 v4, v3, v2
	v_cndmask_b32_e32 v3, v3, v4, vcc
	v_add_u32_e32 v4, 1, v1
	v_cmp_ge_u32_e32 vcc, v3, v2
	v_add_u32_e32 v3, 1, v5
	s_nop 0
	v_cndmask_b32_e32 v1, v1, v4, vcc
	v_mul_lo_u32 v4, v2, v1
	v_add_u32_e32 v2, v4, v2
	v_cmp_ne_u32_e32 vcc, v3, v2
	s_and_saveexec_b64 s[6:7], vcc
	s_xor_b64 s[6:7], exec, s[6:7]
	s_cbranch_execz .LBB0_80
	s_waitcnt lgkmcnt(0)
	buffer_inv sc1
	v_mov_b32_e32 v0, 0x2000
	global_load_dword v0, v0, s[4:5] offset:1024 sc1
	s_add_u32 s14, s4, 0x2400
	s_addc_u32 s15, s5, 0
	s_waitcnt vmcnt(0)
	v_cmp_eq_u32_e32 vcc, v0, v1
	s_and_saveexec_b64 s[8:9], vcc
	s_cbranch_execz .LBB0_79
	s_add_u32 s12, s68, 0x80200
	s_addc_u32 s13, s69, 0
	s_mov_b32 s3, 1
	s_mov_b64 s[16:17], 0
	v_mov_b32_e32 v0, 0
	s_branch .LBB0_70

; __device__ __forceinline__ unsigned xb_ld(unsigned* p)              { return __hip_atomic_load(p, __ATOMIC_RELAXED, __HIP_MEMORY_SCOPE_AGENT); }
; __device__ __forceinline__ unsigned xb_add(unsigned* p, unsigned v) { return __hip_atomic_fetch_add(p, v, __ATOMIC_RELAXED, __HIP_MEMORY_SCOPE_AGENT); }
; #define XB_SPIN(cond, bar) do { unsigned _sp = 0; while (cond) { __builtin_amdgcn_s_sleep(1); \
;     if ((++_sp & 255u) == 0u) { if (xb_ld(&(bar)[XB_TMO])) break; if (_sp > XB_SPIN_CAP) { atomicAdd(&(bar)[XB_TMO], 1u); break; } } } } while (0)
; __device__ __forceinline__ void xcd_barrier(const XcdBarrier& b) {
;     ...
;         if (old + 1u == (gen + 1u) * nloc) {
;             __builtin_amdgcn_fence(__ATOMIC_RELEASE, "agent");
;             asm volatile("s_waitcnt vmcnt(0)" ::: "memory");
;             const unsigned og = xb_add(&bar[XB_TOP], 1u);
;             const unsigned tg = og / nx;
;             if (og + 1u == (tg + 1u) * nx) xb_add(&bar[XB_TOPGEN], 1u);
;             else XB_SPIN(xb_ld(&bar[XB_TOPGEN]) == tg, bar);
;             __builtin_amdgcn_fence(__ATOMIC_ACQUIRE, "agent");
;             xb_add(&bar[XB_XGEN(b.x)], 1u);
;             asm volatile("s_waitcnt vmcnt(0)" ::: "memory");
;         } else {
;             XB_SPIN(xb_ld(&bar[XB_XGEN(b.x)]) == gen, bar);
;             __builtin_amdgcn_fence(__ATOMIC_ACQUIRE, "agent");
;             asm volatile("s_waitcnt vmcnt(0)" ::: "memory");
.LBB0_79:
	s_or_b64 exec, exec, s[8:9]
	s_waitcnt vmcnt(0)
	s_waitcnt vmcnt(0)
.LBB0_80:
	s_andn2_saveexec_b64 s[6:7], s[6:7]
	s_cbranch_execz .LBB0_100
	s_mov_b64 s[6:7], exec
	buffer_inv sc1
	buffer_wbl2 sc1
	s_waitcnt lgkmcnt(0)
	s_waitcnt vmcnt(0)
	v_mbcnt_lo_u32_b32 v1, s6, 0
	v_mbcnt_hi_u32_b32 v1, s7, v1
	v_cmp_eq_u32_e32 vcc, 0, v1
	s_and_saveexec_b64 s[8:9], vcc
	s_cbranch_execz .LBB0_83
	s_bcnt1_i32_b64 s3, s[6:7]
	v_mov_b32_e32 v2, 0x83000
	v_mov_b32_e32 v3, s3
	global_atomic_add v2, v2, v3, s[68:69] offset:1024 sc0

; __device__ __forceinline__ unsigned xb_ld(unsigned* p)              { return __hip_atomic_load(p, __ATOMIC_RELAXED, __HIP_MEMORY_SCOPE_AGENT); }
; __device__ __forceinline__ unsigned xb_add(unsigned* p, unsigned v) { return __hip_atomic_fetch_add(p, v, __ATOMIC_RELAXED, __HIP_MEMORY_SCOPE_AGENT); }
; #define XB_SPIN(cond, bar) do { unsigned _sp = 0; while (cond) { __builtin_amdgcn_s_sleep(1); \
;     if ((++_sp & 255u) == 0u) { if (xb_ld(&(bar)[XB_TMO])) break; if (_sp > XB_SPIN_CAP) { atomicAdd(&(bar)[XB_TMO], 1u); break; } } } } while (0)
; __device__ __forceinline__ void xcd_barrier(const XcdBarrier& b) {
;     ...
;             const unsigned og = xb_add(&bar[XB_TOP], 1u);
;             const unsigned tg = og / nx;
;             if (og + 1u == (tg + 1u) * nx) xb_add(&bar[XB_TOPGEN], 1u);
;             else XB_SPIN(xb_ld(&bar[XB_TOPGEN]) == tg, bar);
;             __builtin_amdgcn_fence(__ATOMIC_ACQUIRE, "agent");
;             xb_add(&bar[XB_XGEN(b.x)], 1u);
.LBB0_97:
	s_or_b64 exec, exec, s[6:7]
	s_mov_b64 s[6:7], exec
	v_mbcnt_lo_u32_b32 v0, s6, 0
	v_mbcnt_hi_u32_b32 v0, s7, v0
	v_cmp_eq_u32_e32 vcc, 0, v0
	s_waitcnt vmcnt(0)
	s_and_saveexec_b64 s[8:9], vcc
	s_cbranch_execz .LBB0_99
	s_bcnt1_i32_b64 s3, s[6:7]
	v_mov_b32_e32 v0, 0x2000
	v_mov_b32_e32 v1, s3
	global_atomic_add v0, v1, s[4:5] offset:1024

; __device__ __forceinline__ unsigned xb_ld(unsigned* p)              { return __hip_atomic_load(p, __ATOMIC_RELAXED, __HIP_MEMORY_SCOPE_AGENT); }
; __device__ __forceinline__ unsigned xb_add(unsigned* p, unsigned v) { return __hip_atomic_fetch_add(p, v, __ATOMIC_RELAXED, __HIP_MEMORY_SCOPE_AGENT); }
; #define XB_SPIN(cond, bar) do { unsigned _sp = 0; while (cond) { __builtin_amdgcn_s_sleep(1); \
;     if ((++_sp & 255u) == 0u) { if (xb_ld(&(bar)[XB_TMO])) break; if (_sp > XB_SPIN_CAP) { atomicAdd(&(bar)[XB_TMO], 1u); break; } } } } while (0)
; __device__ __forceinline__ void xcd_barrier(const XcdBarrier& b) {
;     ...
;         const unsigned old = xb_add(&bar[XB_XSUB(b.x)], 1u);
;         const unsigned gen = old / nloc;
;         if (old + 1u == (gen + 1u) * nloc) {
;             __builtin_amdgcn_fence(__ATOMIC_RELEASE, "agent");
;             asm volatile("s_waitcnt vmcnt(0)" ::: "memory");
;             const unsigned og = xb_add(&bar[XB_TOP], 1u);
;             const unsigned tg = og / nx;
;             if (og + 1u == (tg + 1u) * nx) xb_add(&bar[XB_TOPGEN], 1u);
;             else XB_SPIN(xb_ld(&bar[XB_TOPGEN]) == tg, bar);
;             __builtin_amdgcn_fence(__ATOMIC_ACQUIRE, "agent");
;             xb_add(&bar[XB_XGEN(b.x)], 1u);
;             asm volatile("s_waitcnt vmcnt(0)" ::: "memory");
;         } else {
;             XB_SPIN(xb_ld(&bar[XB_XGEN(b.x)]) == gen, bar);
.LBB0_636:
	s_or_b64 exec, exec, s[8:9]
	v_cvt_f32_u32_e32 v4, v2
	s_waitcnt vmcnt(0)
	v_readfirstlane_b32 s3, v3
	v_sub_u32_e32 v3, 0, v2
	v_rcp_iflag_f32_e32 v4, v4
	v_add_u32_e32 v5, s3, v1
	v_mul_f32_e32 v4, 0x4f7ffffe, v4
	v_cvt_u32_f32_e32 v4, v4
	v_mul_lo_u32 v1, v3, v4
	v_mul_hi_u32 v1, v4, v1
	v_add_u32_e32 v1, v4, v1
	v_mul_hi_u32 v1, v5, v1
	v_mul_lo_u32 v3, v1, v2
	v_sub_u32_e32 v3, v5, v3
	v_add_u32_e32 v4, 1, v1
	v_cmp_ge_u32_e32 vcc, v3, v2
	s_nop 1
	v_cndmask_b32_e32 v1, v1, v4, vcc
	v_sub_u32_e32 v4, v3, v2
	v_cndmask_b32_e32 v3, v3, v4, vcc
	v_add_u32_e32 v4, 1, v1
	v_cmp_ge_u32_e32 vcc, v3, v2
	v_add_u32_e32 v3, 1, v5
	s_nop 0
	v_cndmask_b32_e32 v1, v1, v4, vcc
	v_mul_lo_u32 v4, v2, v1
	v_add_u32_e32 v2, v4, v2
	v_cmp_ne_u32_e32 vcc, v3, v2
	s_and_saveexec_b64 s[6:7], vcc
	s_xor_b64 s[6:7], exec, s[6:7]
	s_cbranch_execz .LBB0_650
	s_waitcnt lgkmcnt(0)
	buffer_inv sc1
	v_mov_b32_e32 v0, 0x2000
	global_load_dword v0, v0, s[4:5] offset:1024 sc1
	s_add_u32 s12, s4, 0x2400
	s_addc_u32 s13, s5, 0
	s_waitcnt vmcnt(0)
	v_cmp_eq_u32_e32 vcc, v0, v1
	s_and_saveexec_b64 s[8:9], vcc
	s_cbranch_execz .LBB0_649
	s_add_u32 s10, s68, 0x80200
	s_addc_u32 s11, s69, 0
	s_mov_b32 s3, 1
	s_mov_b64 s[14:15], 0
	v_mov_b32_e32 v0, 0
	s_branch .LBB0_640

; __device__ __forceinline__ unsigned xb_ld(unsigned* p)              { return __hip_atomic_load(p, __ATOMIC_RELAXED, __HIP_MEMORY_SCOPE_AGENT); }
; __device__ __forceinline__ unsigned xb_add(unsigned* p, unsigned v) { return __hip_atomic_fetch_add(p, v, __ATOMIC_RELAXED, __HIP_MEMORY_SCOPE_AGENT); }
; #define XB_SPIN(cond, bar) do { unsigned _sp = 0; while (cond) { __builtin_amdgcn_s_sleep(1); \
;     if ((++_sp & 255u) == 0u) { if (xb_ld(&(bar)[XB_TMO])) break; if (_sp > XB_SPIN_CAP) { atomicAdd(&(bar)[XB_TMO], 1u); break; } } } } while (0)
; __device__ __forceinline__ void xcd_barrier(const XcdBarrier& b) {
;     ...
;         const unsigned old = xb_add(&bar[XB_XSUB(b.x)], 1u);
;         const unsigned gen = old / nloc;
;         if (old + 1u == (gen + 1u) * nloc) {
;             __builtin_amdgcn_fence(__ATOMIC_RELEASE, "agent");
;             asm volatile("s_waitcnt vmcnt(0)" ::: "memory");
;             const unsigned og = xb_add(&bar[XB_TOP], 1u);
;             const unsigned tg = og / nx;
;             if (og + 1u == (tg + 1u) * nx) xb_add(&bar[XB_TOPGEN], 1u);
;             else XB_SPIN(xb_ld(&bar[XB_TOPGEN]) == tg, bar);
;             __builtin_amdgcn_fence(__ATOMIC_ACQUIRE, "agent");
;             xb_add(&bar[XB_XGEN(b.x)], 1u);
;             asm volatile("s_waitcnt vmcnt(0)" ::: "memory");
;         } else {
;             XB_SPIN(xb_ld(&bar[XB_XGEN(b.x)]) == gen, bar);
.LBB0_934:
	s_or_b64 exec, exec, s[14:15]
	v_cvt_f32_u32_e32 v4, v2
	s_waitcnt vmcnt(0)
	v_readfirstlane_b32 s3, v3
	v_sub_u32_e32 v3, 0, v2
	v_rcp_iflag_f32_e32 v4, v4
	v_add_u32_e32 v5, s3, v1
	v_mul_f32_e32 v4, 0x4f7ffffe, v4
	v_cvt_u32_f32_e32 v4, v4
	v_mul_lo_u32 v1, v3, v4
	v_mul_hi_u32 v1, v4, v1
	v_add_u32_e32 v1, v4, v1
	v_mul_hi_u32 v1, v5, v1
	v_mul_lo_u32 v3, v1, v2
	v_sub_u32_e32 v3, v5, v3
	v_add_u32_e32 v4, 1, v1
	v_cmp_ge_u32_e32 vcc, v3, v2
	s_nop 1
	v_cndmask_b32_e32 v1, v1, v4, vcc
	v_sub_u32_e32 v4, v3, v2
	v_cndmask_b32_e32 v3, v3, v4, vcc
	v_add_u32_e32 v4, 1, v1
	v_cmp_ge_u32_e32 vcc, v3, v2
	v_add_u32_e32 v3, 1, v5
	s_nop 0
	v_cndmask_b32_e32 v1, v1, v4, vcc
	v_mul_lo_u32 v4, v2, v1
	v_add_u32_e32 v2, v4, v2
	v_cmp_ne_u32_e32 vcc, v3, v2
	s_and_saveexec_b64 s[12:13], vcc
	s_xor_b64 s[12:13], exec, s[12:13]
	s_cbranch_execz .LBB0_948
	s_waitcnt lgkmcnt(0)
	buffer_inv sc1
	v_mov_b32_e32 v0, 0x2000
	global_load_dword v0, v0, s[4:5] offset:1024 sc1
	s_add_u32 s18, s4, 0x2400
	s_addc_u32 s19, s5, 0
	s_waitcnt vmcnt(0)
	v_cmp_eq_u32_e32 vcc, v0, v1
	s_and_saveexec_b64 s[14:15], vcc
	s_cbranch_execz .LBB0_947
	s_add_u32 s16, s68, 0x80200
	s_addc_u32 s17, s69, 0
	s_mov_b32 s3, 1
	s_mov_b64 s[20:21], 0
	v_mov_b32_e32 v0, 0
	s_branch .LBB0_938

; __device__ __forceinline__ unsigned xb_ld(unsigned* p)              { return __hip_atomic_load(p, __ATOMIC_RELAXED, __HIP_MEMORY_SCOPE_AGENT); }
; __device__ __forceinline__ unsigned xb_add(unsigned* p, unsigned v) { return __hip_atomic_fetch_add(p, v, __ATOMIC_RELAXED, __HIP_MEMORY_SCOPE_AGENT); }
; #define XB_SPIN(cond, bar) do { unsigned _sp = 0; while (cond) { __builtin_amdgcn_s_sleep(1); \
;     if ((++_sp & 255u) == 0u) { if (xb_ld(&(bar)[XB_TMO])) break; if (_sp > XB_SPIN_CAP) { atomicAdd(&(bar)[XB_TMO], 1u); break; } } } } while (0)
; __device__ __forceinline__ void xcd_barrier(const XcdBarrier& b) {
;     ...
;         if (old + 1u == (gen + 1u) * nloc) {
;             __builtin_amdgcn_fence(__ATOMIC_RELEASE, "agent");
;             asm volatile("s_waitcnt vmcnt(0)" ::: "memory");
;             const unsigned og = xb_add(&bar[XB_TOP], 1u);
;             const unsigned tg = og / nx;
;             if (og + 1u == (tg + 1u) * nx) xb_add(&bar[XB_TOPGEN], 1u);
;             else XB_SPIN(xb_ld(&bar[XB_TOPGEN]) == tg, bar);
;             __builtin_amdgcn_fence(__ATOMIC_ACQUIRE, "agent");
;             xb_add(&bar[XB_XGEN(b.x)], 1u);
;             asm volatile("s_waitcnt vmcnt(0)" ::: "memory");
;         } else {
;             XB_SPIN(xb_ld(&bar[XB_XGEN(b.x)]) == gen, bar);
;             __builtin_amdgcn_fence(__ATOMIC_ACQUIRE, "agent");
;             asm volatile("s_waitcnt vmcnt(0)" ::: "memory");
.LBB0_947:
	s_or_b64 exec, exec, s[14:15]
	s_waitcnt vmcnt(0)
	s_waitcnt vmcnt(0)
.LBB0_948:
	s_andn2_saveexec_b64 s[12:13], s[12:13]
	s_cbranch_execz .LBB0_968
	s_mov_b64 s[12:13], exec
	buffer_inv sc1
	buffer_wbl2 sc1
	s_waitcnt lgkmcnt(0)
	s_waitcnt vmcnt(0)
	v_mbcnt_lo_u32_b32 v1, s12, 0
	v_mbcnt_hi_u32_b32 v1, s13, v1
	v_cmp_eq_u32_e32 vcc, 0, v1
	s_and_saveexec_b64 s[14:15], vcc
	s_cbranch_execz .LBB0_951
	s_bcnt1_i32_b64 s3, s[12:13]
	v_mov_b32_e32 v2, 0x83000
	v_mov_b32_e32 v3, s3
	global_atomic_add v2, v2, v3, s[68:69] offset:1024 sc0

; __device__ __forceinline__ unsigned xb_ld(unsigned* p)              { return __hip_atomic_load(p, __ATOMIC_RELAXED, __HIP_MEMORY_SCOPE_AGENT); }
; __device__ __forceinline__ unsigned xb_add(unsigned* p, unsigned v) { return __hip_atomic_fetch_add(p, v, __ATOMIC_RELAXED, __HIP_MEMORY_SCOPE_AGENT); }
; #define XB_SPIN(cond, bar) do { unsigned _sp = 0; while (cond) { __builtin_amdgcn_s_sleep(1); \
;     if ((++_sp & 255u) == 0u) { if (xb_ld(&(bar)[XB_TMO])) break; if (_sp > XB_SPIN_CAP) { atomicAdd(&(bar)[XB_TMO], 1u); break; } } } } while (0)
; __device__ __forceinline__ void xcd_barrier(const XcdBarrier& b) {
;     ...
;             const unsigned og = xb_add(&bar[XB_TOP], 1u);
;             const unsigned tg = og / nx;
;             if (og + 1u == (tg + 1u) * nx) xb_add(&bar[XB_TOPGEN], 1u);
;             else XB_SPIN(xb_ld(&bar[XB_TOPGEN]) == tg, bar);
;             __builtin_amdgcn_fence(__ATOMIC_ACQUIRE, "agent");
;             xb_add(&bar[XB_XGEN(b.x)], 1u);
.LBB0_965:
	s_or_b64 exec, exec, s[12:13]
	s_mov_b64 s[12:13], exec
	v_mbcnt_lo_u32_b32 v0, s12, 0
	v_mbcnt_hi_u32_b32 v0, s13, v0
	v_cmp_eq_u32_e32 vcc, 0, v0
	s_waitcnt vmcnt(0)
	s_and_saveexec_b64 s[14:15], vcc
	s_cbranch_execz .LBB0_967
	s_bcnt1_i32_b64 s3, s[12:13]
	v_mov_b32_e32 v0, 0x2000
	v_mov_b32_e32 v1, s3
	global_atomic_add v0, v1, s[4:5] offset:1024

; __device__ __forceinline__ unsigned xb_ld(unsigned* p)              { return __hip_atomic_load(p, __ATOMIC_RELAXED, __HIP_MEMORY_SCOPE_AGENT); }
; __device__ __forceinline__ unsigned xb_add(unsigned* p, unsigned v) { return __hip_atomic_fetch_add(p, v, __ATOMIC_RELAXED, __HIP_MEMORY_SCOPE_AGENT); }
; #define XB_SPIN(cond, bar) do { unsigned _sp = 0; while (cond) { __builtin_amdgcn_s_sleep(1); \
;     if ((++_sp & 255u) == 0u) { if (xb_ld(&(bar)[XB_TMO])) break; if (_sp > XB_SPIN_CAP) { atomicAdd(&(bar)[XB_TMO], 1u); break; } } } } while (0)
; __device__ __forceinline__ void xcd_barrier(const XcdBarrier& b) {
;     ...
;         const unsigned old = xb_add(&bar[XB_XSUB(b.x)], 1u);
;         const unsigned gen = old / nloc;
;         if (old + 1u == (gen + 1u) * nloc) {
;             __builtin_amdgcn_fence(__ATOMIC_RELEASE, "agent");
;             asm volatile("s_waitcnt vmcnt(0)" ::: "memory");
;             const unsigned og = xb_add(&bar[XB_TOP], 1u);
;             const unsigned tg = og / nx;
;             if (og + 1u == (tg + 1u) * nx) xb_add(&bar[XB_TOPGEN], 1u);
;             else XB_SPIN(xb_ld(&bar[XB_TOPGEN]) == tg, bar);
;             __builtin_amdgcn_fence(__ATOMIC_ACQUIRE, "agent");
;             xb_add(&bar[XB_XGEN(b.x)], 1u);
;             asm volatile("s_waitcnt vmcnt(0)" ::: "memory");
;         } else {
;             XB_SPIN(xb_ld(&bar[XB_XGEN(b.x)]) == gen, bar);
.LBB0_1002:
	s_or_b64 exec, exec, s[14:15]
	v_cvt_f32_u32_e32 v4, v2
	s_waitcnt vmcnt(0)
	v_readfirstlane_b32 s3, v3
	v_sub_u32_e32 v3, 0, v2
	v_rcp_iflag_f32_e32 v4, v4
	v_add_u32_e32 v5, s3, v1
	v_mul_f32_e32 v4, 0x4f7ffffe, v4
	v_cvt_u32_f32_e32 v4, v4
	v_mul_lo_u32 v1, v3, v4
	v_mul_hi_u32 v1, v4, v1
	v_add_u32_e32 v1, v4, v1
	v_mul_hi_u32 v1, v5, v1
	v_mul_lo_u32 v3, v1, v2
	v_sub_u32_e32 v3, v5, v3
	v_add_u32_e32 v4, 1, v1
	v_cmp_ge_u32_e32 vcc, v3, v2
	s_nop 1
	v_cndmask_b32_e32 v1, v1, v4, vcc
	v_sub_u32_e32 v4, v3, v2
	v_cndmask_b32_e32 v3, v3, v4, vcc
	v_add_u32_e32 v4, 1, v1
	v_cmp_ge_u32_e32 vcc, v3, v2
	v_add_u32_e32 v3, 1, v5
	s_nop 0
	v_cndmask_b32_e32 v1, v1, v4, vcc
	v_mul_lo_u32 v4, v2, v1
	v_add_u32_e32 v2, v4, v2
	v_cmp_ne_u32_e32 vcc, v3, v2
	s_and_saveexec_b64 s[12:13], vcc
	s_xor_b64 s[12:13], exec, s[12:13]
	s_cbranch_execz .LBB0_1016
	s_waitcnt lgkmcnt(0)
	buffer_inv sc1
	v_mov_b32_e32 v0, 0x2000
	global_load_dword v0, v0, s[10:11] offset:1024 sc1
	s_add_u32 s18, s10, 0x2400
	s_addc_u32 s19, s11, 0
	s_waitcnt vmcnt(0)
	v_cmp_eq_u32_e32 vcc, v0, v1
	s_and_saveexec_b64 s[14:15], vcc
	s_cbranch_execz .LBB0_1015
	s_add_u32 s16, s68, 0x80200
	s_addc_u32 s17, s69, 0
	s_mov_b32 s3, 1
	s_mov_b64 s[20:21], 0
	v_mov_b32_e32 v0, 0
	s_branch .LBB0_1006

; __device__ __forceinline__ unsigned xb_ld(unsigned* p)              { return __hip_atomic_load(p, __ATOMIC_RELAXED, __HIP_MEMORY_SCOPE_AGENT); }
; __device__ __forceinline__ unsigned xb_add(unsigned* p, unsigned v) { return __hip_atomic_fetch_add(p, v, __ATOMIC_RELAXED, __HIP_MEMORY_SCOPE_AGENT); }
; #define XB_SPIN(cond, bar) do { unsigned _sp = 0; while (cond) { __builtin_amdgcn_s_sleep(1); \
;     if ((++_sp & 255u) == 0u) { if (xb_ld(&(bar)[XB_TMO])) break; if (_sp > XB_SPIN_CAP) { atomicAdd(&(bar)[XB_TMO], 1u); break; } } } } while (0)
; __device__ __forceinline__ void xcd_barrier(const XcdBarrier& b) {
;     ...
;             const unsigned og = xb_add(&bar[XB_TOP], 1u);
;             const unsigned tg = og / nx;
;             if (og + 1u == (tg + 1u) * nx) xb_add(&bar[XB_TOPGEN], 1u);
;             else XB_SPIN(xb_ld(&bar[XB_TOPGEN]) == tg, bar);
;             __builtin_amdgcn_fence(__ATOMIC_ACQUIRE, "agent");
;             xb_add(&bar[XB_XGEN(b.x)], 1u);
.LBB0_1033:
	s_or_b64 exec, exec, s[12:13]
	s_mov_b64 s[12:13], exec
	v_mbcnt_lo_u32_b32 v0, s12, 0
	v_mbcnt_hi_u32_b32 v0, s13, v0
	v_cmp_eq_u32_e32 vcc, 0, v0
	s_waitcnt vmcnt(0)
	s_and_saveexec_b64 s[14:15], vcc
	s_cbranch_execz .LBB0_1035
	s_bcnt1_i32_b64 s3, s[12:13]
	v_mov_b32_e32 v0, 0x2000
	v_mov_b32_e32 v1, s3
	global_atomic_add v0, v1, s[10:11] offset:1024

; __device__ __forceinline__ unsigned xb_ld(unsigned* p)              { return __hip_atomic_load(p, __ATOMIC_RELAXED, __HIP_MEMORY_SCOPE_AGENT); }
; __device__ __forceinline__ unsigned xb_add(unsigned* p, unsigned v) { return __hip_atomic_fetch_add(p, v, __ATOMIC_RELAXED, __HIP_MEMORY_SCOPE_AGENT); }
; #define XB_SPIN(cond, bar) do { unsigned _sp = 0; while (cond) { __builtin_amdgcn_s_sleep(1); \
;     if ((++_sp & 255u) == 0u) { if (xb_ld(&(bar)[XB_TMO])) break; if (_sp > XB_SPIN_CAP) { atomicAdd(&(bar)[XB_TMO], 1u); break; } } } } while (0)
; __device__ __forceinline__ void xcd_barrier(const XcdBarrier& b) {
;     ...
;         const unsigned old = xb_add(&bar[XB_XSUB(b.x)], 1u);
;         const unsigned gen = old / nloc;
;         if (old + 1u == (gen + 1u) * nloc) {
;             __builtin_amdgcn_fence(__ATOMIC_RELEASE, "agent");
;             asm volatile("s_waitcnt vmcnt(0)" ::: "memory");
;             const unsigned og = xb_add(&bar[XB_TOP], 1u);
;             const unsigned tg = og / nx;
;             if (og + 1u == (tg + 1u) * nx) xb_add(&bar[XB_TOPGEN], 1u);
;             else XB_SPIN(xb_ld(&bar[XB_TOPGEN]) == tg, bar);
;             __builtin_amdgcn_fence(__ATOMIC_ACQUIRE, "agent");
;             xb_add(&bar[XB_XGEN(b.x)], 1u);
;             asm volatile("s_waitcnt vmcnt(0)" ::: "memory");
;         } else {
;             XB_SPIN(xb_ld(&bar[XB_XGEN(b.x)]) == gen, bar);
.LBB0_1120:
	s_or_b64 exec, exec, s[8:9]
	v_cvt_f32_u32_e32 v4, v2
	s_waitcnt vmcnt(0)
	v_readfirstlane_b32 s4, v3
	v_sub_u32_e32 v3, 0, v2
	v_rcp_iflag_f32_e32 v4, v4
	v_add_u32_e32 v5, s4, v1
	v_mul_f32_e32 v4, 0x4f7ffffe, v4
	v_cvt_u32_f32_e32 v4, v4
	v_mul_lo_u32 v1, v3, v4
	v_mul_hi_u32 v1, v4, v1
	v_add_u32_e32 v1, v4, v1
	v_mul_hi_u32 v1, v5, v1
	v_mul_lo_u32 v3, v1, v2
	v_sub_u32_e32 v3, v5, v3
	v_add_u32_e32 v4, 1, v1
	v_cmp_ge_u32_e32 vcc, v3, v2
	s_nop 1
	v_cndmask_b32_e32 v1, v1, v4, vcc
	v_sub_u32_e32 v4, v3, v2
	v_cndmask_b32_e32 v3, v3, v4, vcc
	v_add_u32_e32 v4, 1, v1
	v_cmp_ge_u32_e32 vcc, v3, v2
	v_add_u32_e32 v3, 1, v5
	s_nop 0
	v_cndmask_b32_e32 v1, v1, v4, vcc
	v_mul_lo_u32 v4, v2, v1
	v_add_u32_e32 v2, v4, v2
	v_cmp_ne_u32_e32 vcc, v3, v2
	s_and_saveexec_b64 s[4:5], vcc
	s_xor_b64 s[4:5], exec, s[4:5]
	s_cbranch_execz .LBB0_1134
	s_waitcnt lgkmcnt(0)
	buffer_inv sc1
	v_mov_b32_e32 v0, 0x2000
	global_load_dword v0, v0, s[2:3] offset:1024 sc1
	s_add_u32 s12, s2, 0x2400
	s_addc_u32 s13, s3, 0
	s_waitcnt vmcnt(0)
	v_cmp_eq_u32_e32 vcc, v0, v1
	s_and_saveexec_b64 s[8:9], vcc
	s_cbranch_execz .LBB0_1133
	s_add_u32 s10, s68, 0x80200
	s_addc_u32 s11, s69, 0
	s_mov_b32 s24, 1
	s_mov_b64 s[14:15], 0
	v_mov_b32_e32 v0, 0
	s_branch .LBB0_1124

; __device__ __forceinline__ unsigned xb_add(unsigned* p, unsigned v) { return __hip_atomic_fetch_add(p, v, __ATOMIC_RELAXED, __HIP_MEMORY_SCOPE_AGENT); }
; __device__ __forceinline__ void xcd_barrier(const XcdBarrier& b) {
;     ...
;         if (old + 1u == (gen + 1u) * nloc) {
;             __builtin_amdgcn_fence(__ATOMIC_RELEASE, "agent");
;             asm volatile("s_waitcnt vmcnt(0)" ::: "memory");
;             const unsigned og = xb_add(&bar[XB_TOP], 1u);
.LBB0_1134:
	s_andn2_saveexec_b64 s[4:5], s[4:5]
	s_cbranch_execz .LBB0_1154
	s_mov_b64 s[4:5], exec
	buffer_inv sc1
	buffer_wbl2 sc1
	s_waitcnt lgkmcnt(0)
	s_waitcnt vmcnt(0)
	v_mbcnt_lo_u32_b32 v1, s4, 0
	v_mbcnt_hi_u32_b32 v1, s5, v1
	v_cmp_eq_u32_e32 vcc, 0, v1
	s_and_saveexec_b64 s[8:9], vcc
	s_cbranch_execz .LBB0_1137
	s_bcnt1_i32_b64 s4, s[4:5]
	v_mov_b32_e32 v2, 0x83000
	v_mov_b32_e32 v3, s4
	global_atomic_add v2, v2, v3, s[68:69] offset:1024 sc0

; __device__ __forceinline__ unsigned xb_ld(unsigned* p)              { return __hip_atomic_load(p, __ATOMIC_RELAXED, __HIP_MEMORY_SCOPE_AGENT); }
; __device__ __forceinline__ unsigned xb_add(unsigned* p, unsigned v) { return __hip_atomic_fetch_add(p, v, __ATOMIC_RELAXED, __HIP_MEMORY_SCOPE_AGENT); }
; #define XB_SPIN(cond, bar) do { unsigned _sp = 0; while (cond) { __builtin_amdgcn_s_sleep(1); \
;     if ((++_sp & 255u) == 0u) { if (xb_ld(&(bar)[XB_TMO])) break; if (_sp > XB_SPIN_CAP) { atomicAdd(&(bar)[XB_TMO], 1u); break; } } } } while (0)
; __device__ __forceinline__ void xcd_barrier(const XcdBarrier& b) {
;     ...
;             const unsigned og = xb_add(&bar[XB_TOP], 1u);
;             const unsigned tg = og / nx;
;             if (og + 1u == (tg + 1u) * nx) xb_add(&bar[XB_TOPGEN], 1u);
;             else XB_SPIN(xb_ld(&bar[XB_TOPGEN]) == tg, bar);
;             __builtin_amdgcn_fence(__ATOMIC_ACQUIRE, "agent");
;             xb_add(&bar[XB_XGEN(b.x)], 1u);
.LBB0_1151:
	s_or_b64 exec, exec, s[4:5]
	s_mov_b64 s[4:5], exec
	v_mbcnt_lo_u32_b32 v0, s4, 0
	v_mbcnt_hi_u32_b32 v0, s5, v0
	v_cmp_eq_u32_e32 vcc, 0, v0
	s_waitcnt vmcnt(0)
	s_and_saveexec_b64 s[8:9], vcc
	s_cbranch_execz .LBB0_1153
	s_bcnt1_i32_b64 s4, s[4:5]
	v_mov_b32_e32 v0, 0x2000
	v_mov_b32_e32 v1, s4
	global_atomic_add v0, v1, s[2:3] offset:1024
